# nt cache policy on weight-conversion loads/stores; partial workgroups convert weights before their in-proj GEMM tiles
# speedup vs baseline: 1.0024x; 1.0024x over previous
.LBB0_6:
	v_writelane_b32 v255, 0, 63
	v_readlane_b32 s0, v254, 1
	v_readlane_b32 s1, v254, 2
	s_add_u32 s0, s0, 0x108
	s_addc_u32 s1, s1, 0
	v_writelane_b32 v254, s0, 5
	v_mbcnt_lo_u32_b32 v2, -1, 0
	v_mov_b32_e32 v191, 0
	v_writelane_b32 v254, s1, 6
	s_add_u32 s0, s92, 0x200
	s_addc_u32 s1, s93, 0
	v_writelane_b32 v254, s0, 7
	v_mbcnt_hi_u32_b32 v221, -1, v2
	s_movk_i32 s33, 0x100
	v_writelane_b32 v254, s1, 8
	s_add_u32 s0, s92, 0x1000
	s_addc_u32 s1, s93, 0
	v_writelane_b32 v254, s0, 9
	v_mov_b64_e32 v[192:193], 0x100
	v_mov_b64_e32 v[194:195], 0xff
	v_writelane_b32 v254, s1, 10
	s_add_u32 s0, s92, 0x1100
	s_addc_u32 s1, s93, 0
	v_writelane_b32 v254, s0, 11
	s_movk_i32 s6, 0x90
	v_mov_b32_e32 v1, 0x358637bd
	v_writelane_b32 v254, s1, 12
	s_add_u32 s0, s92, 0x1200
	s_addc_u32 s1, s93, 0
	v_writelane_b32 v254, s0, 13
	v_mov_b32_e32 v220, 0x260
	v_mov_b32_e32 v222, 0x3a27c5ac
	v_writelane_b32 v254, s1, 14
	s_add_u32 s0, s92, 0x1300
	s_addc_u32 s1, s93, 0
	v_writelane_b32 v254, s0, 15
	s_cmp_eq_u32 s4, 15
	v_mov_b32_e32 v223, 0x3ecc95a3
	v_writelane_b32 v254, s1, 16
	s_cselect_b64 s[0:1], -1, 0
	v_writelane_b32 v254, s0, 17
	s_cmp_eq_u32 s4, 14
	v_mov_b32_e32 v224, 0x3c0881c4
	v_writelane_b32 v254, s1, 18
	s_cselect_b64 s[0:1], -1, 0
	v_writelane_b32 v254, s0, 19
	s_cmp_eq_u32 s4, 13
	v_mov_b32_e32 v225, 0xbab64f3b
	v_writelane_b32 v254, s1, 20
	s_cselect_b64 s[0:1], -1, 0
	v_writelane_b32 v254, s0, 21
	s_cmp_eq_u32 s4, 12
	v_mov_b32_e32 v2, v191
	v_writelane_b32 v254, s1, 22
	s_cselect_b64 s[0:1], -1, 0
	v_writelane_b32 v254, s0, 23
	s_cmp_eq_u32 s4, 11
	v_mov_b32_e32 v3, v191
	v_writelane_b32 v254, s1, 24
	s_cselect_b64 s[0:1], -1, 0
	v_writelane_b32 v254, s0, 25
	s_cmp_eq_u32 s4, 10
	v_mov_b32_e32 v4, v191
	v_writelane_b32 v254, s1, 26
	s_cselect_b64 s[0:1], -1, 0
	v_writelane_b32 v254, s0, 27
	s_cmp_eq_u32 s4, 9
	v_mov_b32_e32 v5, v191
	v_writelane_b32 v254, s1, 28
	s_cselect_b64 s[0:1], -1, 0
	v_writelane_b32 v254, s0, 29
	s_cmp_eq_u32 s4, 8
	v_mov_b32_e32 v227, 0x42800000
	v_writelane_b32 v254, s1, 30
	s_cselect_b64 s[0:1], -1, 0
	v_writelane_b32 v254, s0, 31
	s_cmp_eq_u32 s4, 7
	v_mov_b32_e32 v228, 0x42000000
	v_writelane_b32 v254, s1, 32
	s_cselect_b64 s[0:1], -1, 0
	v_writelane_b32 v254, s0, 33
	s_cmp_eq_u32 s4, 6
	v_mov_b32_e32 v229, 0x7f800000
	v_writelane_b32 v254, s1, 34
	s_cselect_b64 s[0:1], -1, 0
	v_writelane_b32 v254, s0, 35
	s_cmp_eq_u32 s4, 5
	v_mov_b32_e32 v196, 0x3f317218
	v_writelane_b32 v254, s1, 36
	s_cselect_b64 s[0:1], -1, 0
	v_writelane_b32 v254, s0, 37
	s_cmp_eq_u32 s4, 4
	v_not_b32_e32 v230, 63
	v_writelane_b32 v254, s1, 38
	s_cselect_b64 s[0:1], -1, 0
	v_writelane_b32 v254, s0, 39
	s_cmp_eq_u32 s4, 3
	v_not_b32_e32 v231, 31
	v_writelane_b32 v254, s1, 40
	s_cselect_b64 s[0:1], -1, 0
	v_writelane_b32 v254, s0, 41
	s_cmp_eq_u32 s4, 2
	v_mov_b32_e32 v232, 0x7fc00000
	v_writelane_b32 v254, s1, 42
	s_cselect_b64 s[0:1], -1, 0
	v_writelane_b32 v254, s0, 43
	s_cmp_eq_u32 s4, 1
	s_movk_i32 s8, 0x180
	v_writelane_b32 v254, s1, 44
	s_cselect_b64 s[0:1], -1, 0
	v_writelane_b32 v254, s0, 45
	s_cmp_eq_u32 s4, 0
	s_movk_i32 s9, 0x3600
	v_writelane_b32 v254, s1, 46
	s_cselect_b64 s[0:1], -1, 0
	v_writelane_b32 v254, s0, 47
	s_mov_b32 s10, 0xf800000
	s_movk_i32 s69, 0x1000
	v_writelane_b32 v254, s1, 48
	s_lshl_b32 s0, s4, 8
	s_add_u32 s0, s92, s0
	s_addc_u32 s1, s93, 0
	s_add_u32 s2, s0, 0x1400
	s_addc_u32 s3, s1, 0
	v_writelane_b32 v254, s2, 49
	s_add_u32 s0, s0, 0x2400
	s_addc_u32 s1, s1, 0
	v_writelane_b32 v254, s3, 50
	v_writelane_b32 v254, s0, 51
	s_movk_i32 s7, 0x110
	s_mov_b32 s34, 0x2aaaaaab
	v_writelane_b32 v254, s1, 52
	s_add_u32 s0, s92, 0x3400
	s_addc_u32 s1, s93, 0
	v_writelane_b32 v254, s0, 53
	s_movk_i32 s28, 0x6ff
	s_mov_b64 s[24:25], 0x200
	v_writelane_b32 v254, s1, 54
	s_add_u32 s0, s92, 0x3500
	s_addc_u32 s1, s93, 0
	v_writelane_b32 v254, s0, 55
	s_add_i32 s35, 0, 0x25400
	s_add_i32 s11, 0, 0x25500
	v_writelane_b32 v254, s1, 56
	s_add_i32 s0, 0, 0x8800
	v_writelane_b32 v254, s0, 57
	s_add_i32 s0, 0, 0x20400
	v_writelane_b32 v254, s0, 58
	s_add_i32 s0, 0, 0x1b200
	v_writelane_b32 v254, s0, 59
	s_add_i32 s0, 0, 0x1c400
	v_writelane_b32 v254, s0, 60
	s_add_i32 s0, 0, 0x14400
	v_writelane_b32 v254, s0, 61
	s_add_i32 s0, 0, 0x15800
	v_writelane_b32 v254, s0, 62
	s_add_i32 s0, 0, 0x16c00
	v_writelane_b32 v254, s0, 63
	s_add_i32 s0, 0, 0x1b000
	v_writelane_b32 v255, s0, 0
	s_add_i32 s0, 0, 0x23000
	v_writelane_b32 v255, s0, 1
	s_add_i32 s0, 0, 0x16800
	v_writelane_b32 v255, s0, 2
	s_add_i32 s0, 0, 0x18c00
	v_writelane_b32 v255, s0, 3
	s_add_i32 s0, 0, 0x9000
	v_writelane_b32 v255, s0, 4
	s_add_i32 s0, 0, 0x10c00
	v_writelane_b32 v255, s0, 5
	s_add_i32 s0, 0, 0x22000
	v_writelane_b32 v255, s0, 6
	s_add_i32 s0, 0, 0x22400
	v_writelane_b32 v255, s0, 7
	s_add_i32 s0, 0, 0x22800
	v_writelane_b32 v255, s0, 8
	s_add_i32 s0, 0, 0x19000
	v_writelane_b32 v255, s0, 9
	s_add_i32 s0, 0, 0x27e20
	v_writelane_b32 v255, s0, 10
	s_add_i32 s0, 0, 0x27e24
	s_add_i32 s96, 0, 0x25600
	s_add_i32 s97, 0, 0x255fc
	s_add_i32 s72, 0, 0x11000
	s_add_i32 s73, 0, 0x17800
	s_add_i32 s76, 0, 0x18800
	s_add_i32 s77, 0, 0x1bc00
	v_writelane_b32 v255, s0, 11
	s_mov_b32 s27, 0
	s_mov_b64 s[30:31], 0x80
	s_mov_b64 s[16:17], 0x400
	s_branch .LBB0_10

.LBB0_1044:
	s_and_b64 vcc, exec, s[4:5]
	s_cbranch_vccz .LBB0_1145
	s_cmpk_lt_i32 s80, 0x60
	s_cbranch_scc1 .Lp1_gemm
	v_readlane_b32 s0, v255, 63
	s_nop 3
	s_cmp_lg_u32 s0, 0
	s_cbranch_scc1 .Lp1_gemm
	v_writelane_b32 v255, 1, 63
	s_branch .Lp1_cvt
.Lp1_gemm:
	s_add_u32 s48, s12, 0x100000
	s_addc_u32 s49, s13, 0
	s_cmpk_gt_i32 s80, 0x35f
	v_readfirstlane_b32 s4, v235
	s_cbranch_scc1 .LBB0_1061
	v_lshlrev_b32_e32 v6, 4, v235
	s_waitcnt lgkmcnt(0)
	v_add_u32_e32 v7, 0x2000, v6
	v_ashrrev_i32_e32 v8, 31, v7
	v_lshrrev_b32_e32 v8, 22, v8
	v_add_u32_e32 v8, v7, v8
	v_ashrrev_i32_e32 v14, 10, v8
	v_mul_i32_i24_e32 v8, 0x400, v14
	v_sub_u32_e32 v7, v7, v8
	v_lshrrev_b32_e32 v8, 4, v7
	v_bitop3_b32 v7, v8, v7, 32 bitop3:0x6c
	v_ashrrev_i32_e32 v8, 31, v7
	v_lshrrev_b32_e32 v8, 26, v8
	v_add_u32_e32 v8, v7, v8
	v_lshlrev_b32_e32 v9, 3, v14
	v_ashrrev_i32_e32 v15, 6, v8
	v_and_b32_e32 v9, -16, v9
	v_add_u32_e32 v9, v15, v9
	v_and_b32_e32 v10, 3, v15
	s_mov_b32 s1, 0xfffe0
	v_lshrrev_b32_e32 v11, 2, v9
	v_lshlrev_b32_e32 v12, 1, v9
	v_and_or_b32 v10, v9, s1, v10
	v_and_b32_e32 v11, 4, v11
	v_and_b32_e32 v12, 24, v12
	v_and_b32_e32 v8, 0xc0, v8
	v_or3_b32 v10, v10, v11, v12
	v_sub_u32_e32 v7, v7, v8
	v_mov_b32_e32 v12, 1
	v_lshlrev_b32_e32 v11, 5, v14
	v_ashrrev_i16_sdwa v7, v12, sext(v7) dst_sel:DWORD dst_unused:UNUSED_PAD src0_sel:DWORD src1_sel:BYTE_0
	v_and_b32_e32 v11, 32, v11
	v_bfe_i32 v16, v7, 0, 16
	v_add_lshl_u32 v7, v11, v16, 1
	v_lshl_add_u32 v134, v10, 12, v7
	v_lshl_add_u32 v136, v9, 12, v7
	v_bfe_i32 v7, v235, 27, 1
	v_lshrrev_b32_e32 v7, 22, v7
	v_add_u32_e32 v7, v6, v7
	v_and_b32_e32 v7, 0xfffffc00, v7
	v_sub_u32_e32 v6, v6, v7
	v_lshrrev_b32_e32 v7, 4, v6
	v_ashrrev_i32_e32 v8, 31, v235
	v_bitop3_b32 v6, v7, v6, 32 bitop3:0x6c
	v_lshrrev_b32_e32 v8, 26, v8
	v_ashrrev_i32_e32 v7, 31, v6
	v_add_u32_e32 v8, v235, v8
	v_lshrrev_b32_e32 v7, 26, v7
	v_ashrrev_i32_e32 v18, 6, v8
	v_add_u32_e32 v7, v6, v7
	v_lshlrev_b32_e32 v8, 3, v18
	v_ashrrev_i32_e32 v17, 6, v7
	v_and_b32_e32 v8, -16, v8
	v_add_u32_e32 v8, v17, v8
	v_and_b32_e32 v9, 3, v17
	v_and_or_b32 v9, v8, s1, v9
	s_ashr_i32 s1, s80, 31
	s_lshr_b32 s2, s1, 29
	s_add_i32 s2, s80, s2
	s_ashr_i32 s21, s4, 6
	s_ashr_i32 s3, s2, 3
	s_and_b32 s2, s2, -8
	s_ashr_i32 s5, s4, 8
	s_lshl_b32 s0, s21, 10
	s_sub_i32 s2, s80, s2
	s_cmp_lt_i32 s2, 0
	s_movk_i32 s14, 0x6d
	s_cselect_b32 s14, s14, 0x6c
	s_mul_i32 s2, s14, s2
	s_add_i32 s2, s2, s3
	s_mul_hi_i32 s3, s2, 0x4bda12f7
	s_lshr_b32 s14, s3, 31
	s_ashr_i32 s3, s3, 6
	s_add_i32 s3, s3, s14
	s_lshl_b32 s14, s3, 3
	s_mulk_i32 s3, 0xd8
	s_sub_i32 s2, s2, s3
	s_bfe_u32 s3, s2, 0x3001c
	s_add_i32 s3, s2, s3
	s_sext_i32_i16 s15, s3
	s_and_b32 s3, s3, 0xfff8
	s_sub_i32 s2, s2, s3
	s_sext_i32_i16 s2, s2
	v_lshrrev_b32_e32 v10, 2, v8
	v_lshlrev_b32_e32 v11, 1, v8
	v_and_b32_e32 v7, 0xc0, v7
	s_lshr_b32 s26, s15, 3
	s_add_i32 s54, s14, s2
	v_and_b32_e32 v10, 4, v10
	v_and_b32_e32 v11, 24, v11
	v_sub_u32_e32 v6, v6, v7
	s_ashr_i32 s55, s54, 31
	s_bfe_i64 s[2:3], s[26:27], 0x100000
	v_or3_b32 v9, v9, v10, v11
	v_lshlrev_b32_e32 v10, 5, v18
	v_ashrrev_i16_sdwa v6, v12, sext(v6) dst_sel:DWORD dst_unused:UNUSED_PAD src0_sel:DWORD src1_sel:BYTE_0
	s_lshl_b64 s[14:15], s[54:55], 20
	s_lshl_b64 s[2:3], s[2:3], 20
	v_and_b32_e32 v10, 32, v10
	v_bfe_i32 v19, v6, 0, 16
	s_add_u32 s56, s48, s2
	v_add_lshl_u32 v6, v10, v19, 1
	s_addc_u32 s57, s49, s3
	s_add_i32 s2, s0, 0
	v_lshl_add_u32 v190, v9, 12, v6
	s_add_i32 m0, s2, 0x10000
	v_lshl_add_u32 v138, v8, 12, v6
	global_load_lds_dwordx4 v190, s[56:57]
	s_add_i32 m0, s2, 0x12000
	s_add_u32 s18, s56, 0x80000
	global_load_lds_dwordx4 v134, s[56:57]
	s_addc_u32 s19, s57, 0
	s_add_i32 m0, s2, 0x14000
	v_mov_b32_e32 v135, v191
	global_load_lds_dwordx4 v190, s[18:19]
	s_add_i32 m0, s2, 0x16000
	v_mov_b32_e32 v139, v191
	global_load_lds_dwordx4 v134, s[18:19]
	v_readlane_b32 s18, v255, 14
	v_readlane_b32 s19, v255, 15
	s_add_u32 s58, s18, s14
	s_addc_u32 s59, s19, s15
	s_add_i32 s3, s2, 0x2000
	s_mov_b32 m0, s2
	s_add_u32 s18, s58, 0x80000
	global_load_lds_dwordx4 v138, s[58:59]
	s_mov_b32 m0, s3
	s_addc_u32 s19, s59, 0
	s_add_i32 s14, s2, 0x4000
	global_load_lds_dwordx4 v136, s[58:59]
	s_mov_b32 m0, s14
	s_add_i32 s15, s2, 0x6000
	global_load_lds_dwordx4 v138, s[18:19]
	s_mov_b32 m0, s15
	v_mov_b32_e32 v137, v191
	global_load_lds_dwordx4 v136, s[18:19]
	s_cmp_eq_u32 s5, 1
	v_lshl_add_u64 v[12:13], s[56:57], 0, v[190:191]
	v_lshl_add_u64 v[10:11], s[56:57], 0, v[134:135]
	v_lshl_add_u64 v[6:7], s[58:59], 0, v[138:139]
	s_cselect_b64 s[18:19], -1, 0
	s_cmp_lg_u32 s5, 1
	v_lshl_add_u64 v[8:9], s[58:59], 0, v[136:137]
	s_cbranch_scc1 .LBB0_1048
	s_barrier

.LBB0_1061:
	s_cmpk_lt_i32 s80, 0x60
	s_cbranch_scc1 .LBB0_1145
	v_readlane_b32 s0, v255, 63
	s_nop 3
	s_cmp_eq_u32 s0, 2
	s_cbranch_scc0 .Lp1_cvt
	v_writelane_b32 v255, 0, 63
	s_branch .LBB0_1145
.Lp1_cvt:
	s_add_i32 s0, s20, 0xfffffd00
	s_cmpk_gt_i32 s0, 0x47ff
	s_cbranch_scc1 .LBB0_1145
	s_load_dwordx8 s[40:47], s[70:71], 0xc8
	s_lshl_b32 s2, s75, 14
	v_and_b32_e32 v50, 31, v235
	v_lshrrev_b32_e32 v51, 5, v234
	v_readlane_b32 s0, v255, 17
	s_add_i32 s18, s2, 0
	v_lshlrev_b32_e32 v6, 2, v50
	s_waitcnt lgkmcnt(0)
	v_mul_u32_u24_e32 v7, 0x84, v51
	v_readlane_b32 s1, v255, 18
	s_mov_b32 s21, s75
	s_ashr_i32 s75, s74, 31
	v_add3_u32 v52, s18, v6, v7
	v_lshlrev_b32_e32 v6, 3, v234
	s_addk_i32 s0, 0xfd00
	s_add_i32 s1, s20, 0x1800
	s_lshl_b64 s[4:5], s[74:75], 26
	v_and_b32_e32 v6, 56, v6
	s_add_u32 s2, s46, s4
	v_lshlrev_b32_e32 v190, 1, v6
	s_addc_u32 s3, s47, s5
	v_lshl_add_u64 v[10:11], s[12:13], 0, v[190:191]
	s_mov_b64 s[14:15], 0x4400000
	v_mul_u32_u24_e32 v8, 0x84, v6
	v_lshl_add_u64 v[6:7], v[10:11], 0, s[14:15]
	s_add_u32 s14, s44, s4
	v_lshrrev_b32_e32 v53, 3, v234
	s_addc_u32 s15, s45, s5
	v_lshlrev_b32_e32 v9, 2, v53
	s_cmp_lg_u64 s[42:43], 0
	v_add3_u32 v54, s18, v8, v9
	s_cselect_b64 s[18:19], -1, 0
	s_lshl_b64 s[4:5], s[74:75], 13
	s_load_dwordx4 s[52:55], s[70:71], 0x8
	s_add_u32 s36, s42, s4
	s_mov_b64 s[38:39], 0x2400000
	s_addc_u32 s37, s43, s5
	v_lshl_add_u64 v[8:9], v[10:11], 0, s[38:39]
	s_lshl_b64 s[38:39], s[74:75], 24
	s_add_u32 s40, s40, s38
	s_addc_u32 s41, s41, s39
	s_mul_i32 s23, s74, 0x3560000
	s_mov_b32 s75, s21
	s_mul_hi_i32 s21, s74, 0x3560000
	s_waitcnt lgkmcnt(0)
	s_add_u32 s42, s54, s23
	s_addc_u32 s43, s55, s21
	s_add_u32 s44, s52, s4
	s_addc_u32 s45, s53, s5
	s_mov_b64 s[38:39], 0x1c00000
	s_cmp_lg_u64 s[52:53], 0
	v_or_b32_e32 v55, 8, v53
	v_or_b32_e32 v56, 16, v53
	v_or_b32_e32 v57, 24, v53
	v_lshl_add_u64 v[10:11], v[10:11], 0, s[38:39]
	s_cselect_b64 s[46:47], -1, 0
	v_lshl_add_u64 v[12:13], s[48:49], 0, v[190:191]
	s_lshl_b32 s21, s1, 5
	s_lshl_b32 s23, s0, 5
	s_branch .LBB0_1066
.LBB0_1064:
	s_waitcnt vmcnt(0)
	ds_write2_b32 v52, v14, v15 offset1:66
	ds_write2_b32 v52, v16, v17 offset0:132 offset1:198
	v_add_u32_e32 v14, 0x400, v52
	ds_write2_b32 v14, v18, v19 offset0:8 offset1:74
	ds_write2_b32 v14, v20, v21 offset0:140 offset1:206
	v_add_u32_e32 v14, 0x800, v52
	ds_write2_b32 v14, v22, v23 offset0:16 offset1:82
	ds_write2_b32 v14, v24, v25 offset0:148 offset1:214
	v_add_u32_e32 v14, 0xc00, v52
	ds_write2_b32 v14, v28, v29 offset0:24 offset1:90
	ds_write2_b32 v14, v32, v33 offset0:156 offset1:222
	v_add_u32_e32 v14, 0x1000, v52
	ds_write2_b32 v14, v34, v35 offset0:32 offset1:98
	ds_write2_b32 v14, v36, v37 offset0:164 offset1:230
	v_add_u32_e32 v14, 0x1400, v52
	ds_write2_b32 v14, v38, v39 offset0:40 offset1:106
	ds_write2_b32 v14, v40, v41 offset0:172 offset1:238
	v_add_u32_e32 v14, 0x1800, v52
	ds_write2_b32 v14, v42, v43 offset0:48 offset1:114
	ds_write2_b32 v14, v44, v45 offset0:180 offset1:246
	v_add_u32_e32 v14, 0x1c00, v52
	ds_write2_b32 v14, v46, v47 offset0:56 offset1:122
	ds_write2_b32 v14, v48, v49 offset0:188 offset1:254
	s_waitcnt lgkmcnt(0)
	ds_read2_b32 v[18:19], v54 offset0:33 offset1:41
	ds_read2_b32 v[20:21], v54 offset1:8
	ds_read2_b32 v[22:23], v54 offset0:66 offset1:74
	ds_read2_b32 v[24:25], v54 offset0:99 offset1:107
	ds_read2_b32 v[26:27], v54 offset0:132 offset1:140
	ds_read2_b32 v[28:29], v54 offset0:165 offset1:173
	ds_read2_b32 v[30:31], v54 offset0:198 offset1:206
	ds_read2_b32 v[32:33], v54 offset0:231 offset1:239
	v_add_u32_e32 v36, s26, v53
	s_ashr_i32 s49, s48, 31
	v_ashrrev_i32_e32 v37, 31, v36
	v_lshl_add_u64 v[34:35], s[48:49], 1, v[12:13]
	v_lshlrev_b64 v[38:39], 12, v[36:37]
	s_waitcnt lgkmcnt(6)
	v_cvt_pk_bf16_f32 v14, v20, v18
	s_waitcnt lgkmcnt(4)
	v_cvt_pk_bf16_f32 v15, v22, v24
	s_waitcnt lgkmcnt(2)
	v_cvt_pk_bf16_f32 v16, v26, v28
	s_waitcnt lgkmcnt(0)
	v_cvt_pk_bf16_f32 v17, v30, v32
	v_lshl_add_u64 v[38:39], v[34:35], 0, v[38:39]
	v_add_u32_e32 v18, 8, v36
	global_store_dwordx4 v[38:39], v[14:17], off nt
	s_nop 1
	v_cvt_pk_bf16_f32 v14, v21, v19
	v_ashrrev_i32_e32 v19, 31, v18
	v_cvt_pk_bf16_f32 v15, v23, v25
	v_cvt_pk_bf16_f32 v16, v27, v29
	v_cvt_pk_bf16_f32 v17, v31, v33
	v_lshlrev_b64 v[18:19], 12, v[18:19]
	ds_read2_b32 v[20:21], v54 offset0:49 offset1:57
	ds_read2_b32 v[22:23], v54 offset0:16 offset1:24
	ds_read2_b32 v[24:25], v54 offset0:82 offset1:90
	ds_read2_b32 v[26:27], v54 offset0:115 offset1:123
	ds_read2_b32 v[28:29], v54 offset0:148 offset1:156
	ds_read2_b32 v[30:31], v54 offset0:181 offset1:189
	ds_read2_b32 v[32:33], v54 offset0:214 offset1:222
	ds_read2_b32 v[38:39], v54 offset0:247 offset1:255
	v_lshl_add_u64 v[18:19], v[34:35], 0, v[18:19]
	global_store_dwordx4 v[18:19], v[14:17], off nt
	v_add_u32_e32 v18, 16, v36
	v_ashrrev_i32_e32 v19, 31, v18
	v_lshlrev_b64 v[18:19], 12, v[18:19]
	s_waitcnt lgkmcnt(6)
	v_cvt_pk_bf16_f32 v14, v22, v20
	s_waitcnt lgkmcnt(4)
	v_cvt_pk_bf16_f32 v15, v24, v26
	s_waitcnt lgkmcnt(2)
	v_cvt_pk_bf16_f32 v16, v28, v30
	s_waitcnt lgkmcnt(0)
	v_cvt_pk_bf16_f32 v17, v32, v38
	v_lshl_add_u64 v[18:19], v[34:35], 0, v[18:19]
	global_store_dwordx4 v[18:19], v[14:17], off nt
	v_add_u32_e32 v18, 24, v36
	v_ashrrev_i32_e32 v19, 31, v18
	v_lshlrev_b64 v[18:19], 12, v[18:19]
	v_cvt_pk_bf16_f32 v14, v23, v21
	v_cvt_pk_bf16_f32 v15, v25, v27
	v_cvt_pk_bf16_f32 v16, v29, v31
	v_cvt_pk_bf16_f32 v17, v33, v39
	v_lshl_add_u64 v[18:19], v[34:35], 0, v[18:19]
	global_store_dwordx4 v[18:19], v[14:17], off nt
	s_waitcnt lgkmcnt(0)

.LBB0_1066:
	s_cmpk_gt_i32 s1, 0x1aff
	s_mov_b64 s[4:5], -1
	s_cbranch_scc0 .LBB0_1078
	s_cmpk_gt_u32 s1, 0x22ff
	s_cbranch_scc0 .LBB0_1075
	s_cmpk_gt_u32 s1, 0x42ff
	s_cbranch_scc0 .LBB0_1070
	s_and_b32 s4, s1, 0x7fffffc0
	s_add_i32 s26, s4, 0xffffbd00
	s_and_b32 s4, s21, 0x7e0
	v_or_b32_e32 v190, s26, v51
	v_or_b32_e32 v16, s4, v50
	v_lshlrev_b64 v[14:15], 13, v[190:191]
	v_lshl_add_u64 v[14:15], s[2:3], 0, v[14:15]
	v_lshlrev_b32_e32 v190, 2, v16
	v_lshl_add_u64 v[14:15], v[14:15], 0, v[190:191]
	v_add_co_u32_e32 v16, vcc, 0x4000, v14
	global_load_dword v18, v[14:15], off nt
	s_nop 0
	v_addc_co_u32_e32 v17, vcc, 0, v15, vcc
	global_load_dword v19, v[16:17], off nt
	v_add_co_u32_e32 v16, vcc, 0x8000, v14
	s_mov_b32 s5, 0x10000
	s_nop 0
	v_addc_co_u32_e32 v17, vcc, 0, v15, vcc
	global_load_dword v20, v[16:17], off nt
	v_add_co_u32_e32 v16, vcc, 0xc000, v14
	s_nop 1
	v_addc_co_u32_e32 v17, vcc, 0, v15, vcc
	global_load_dword v21, v[16:17], off nt
	v_add_co_u32_e32 v16, vcc, s5, v14
	s_mov_b32 s5, 0x14000
	s_nop 0
	v_addc_co_u32_e32 v17, vcc, 0, v15, vcc
	global_load_dword v22, v[16:17], off nt
	v_add_co_u32_e32 v16, vcc, s5, v14
	s_mov_b32 s5, 0x18000
	s_nop 0
	v_addc_co_u32_e32 v17, vcc, 0, v15, vcc
	global_load_dword v23, v[16:17], off nt
	v_add_co_u32_e32 v16, vcc, s5, v14
	s_mov_b32 s5, 0x1c000
	s_nop 0
	v_addc_co_u32_e32 v17, vcc, 0, v15, vcc
	global_load_dword v24, v[16:17], off nt
	v_add_co_u32_e32 v16, vcc, s5, v14
	s_mov_b32 s5, 0x20000
	s_nop 0
	v_addc_co_u32_e32 v17, vcc, 0, v15, vcc
	global_load_dword v25, v[16:17], off nt
	v_add_co_u32_e32 v16, vcc, s5, v14
	s_mov_b32 s5, 0x24000
	s_nop 0
	v_addc_co_u32_e32 v17, vcc, 0, v15, vcc
	global_load_dword v26, v[16:17], off nt
	v_add_co_u32_e32 v16, vcc, s5, v14
	s_mov_b32 s5, 0x28000
	s_nop 0
	v_addc_co_u32_e32 v17, vcc, 0, v15, vcc
	global_load_dword v27, v[16:17], off nt
	v_add_co_u32_e32 v16, vcc, s5, v14
	s_mov_b32 s5, 0x2c000
	s_nop 0
	v_addc_co_u32_e32 v17, vcc, 0, v15, vcc
	global_load_dword v28, v[16:17], off nt
	v_add_co_u32_e32 v16, vcc, s5, v14
	s_mov_b32 s5, 0x30000
	s_nop 0
	v_addc_co_u32_e32 v17, vcc, 0, v15, vcc
	global_load_dword v29, v[16:17], off nt
	v_add_co_u32_e32 v16, vcc, s5, v14
	s_mov_b32 s5, 0x34000
	s_nop 0
	v_addc_co_u32_e32 v17, vcc, 0, v15, vcc
	global_load_dword v30, v[16:17], off nt
	v_add_co_u32_e32 v16, vcc, s5, v14
	s_mov_b32 s5, 0x38000
	s_nop 0
	v_addc_co_u32_e32 v17, vcc, 0, v15, vcc
	global_load_dword v31, v[16:17], off nt
	v_add_co_u32_e32 v16, vcc, s5, v14
	s_mov_b32 s5, 0x3c000
	s_nop 0
	v_addc_co_u32_e32 v17, vcc, 0, v15, vcc
	global_load_dword v32, v[16:17], off nt
	v_add_co_u32_e32 v16, vcc, s5, v14
	s_mov_b32 s5, 0x40000
	s_nop 0
	v_addc_co_u32_e32 v17, vcc, 0, v15, vcc
	global_load_dword v33, v[16:17], off nt
	v_add_co_u32_e32 v16, vcc, s5, v14
	s_mov_b32 s5, 0x44000
	s_nop 0
	v_addc_co_u32_e32 v17, vcc, 0, v15, vcc
	global_load_dword v34, v[16:17], off nt
	v_add_co_u32_e32 v16, vcc, s5, v14
	s_mov_b32 s5, 0x48000
	s_nop 0
	v_addc_co_u32_e32 v17, vcc, 0, v15, vcc
	global_load_dword v35, v[16:17], off nt
	v_add_co_u32_e32 v16, vcc, s5, v14
	s_mov_b32 s5, 0x4c000
	s_nop 0
	v_addc_co_u32_e32 v17, vcc, 0, v15, vcc
	global_load_dword v36, v[16:17], off nt
	v_add_co_u32_e32 v16, vcc, s5, v14
	s_mov_b32 s5, 0x50000
	s_nop 0
	v_addc_co_u32_e32 v17, vcc, 0, v15, vcc
	global_load_dword v37, v[16:17], off nt
	v_add_co_u32_e32 v16, vcc, s5, v14
	s_mov_b32 s5, 0x54000
	s_nop 0
	v_addc_co_u32_e32 v17, vcc, 0, v15, vcc
	global_load_dword v38, v[16:17], off nt
	v_add_co_u32_e32 v16, vcc, s5, v14
	s_mov_b32 s5, 0x58000
	s_nop 0
	v_addc_co_u32_e32 v17, vcc, 0, v15, vcc
	global_load_dword v39, v[16:17], off nt
	v_add_co_u32_e32 v16, vcc, s5, v14
	s_mov_b32 s5, 0x5c000
	s_nop 0
	v_addc_co_u32_e32 v17, vcc, 0, v15, vcc
	global_load_dword v40, v[16:17], off nt
	v_add_co_u32_e32 v16, vcc, s5, v14
	s_mov_b32 s5, 0x60000
	s_nop 0
	v_addc_co_u32_e32 v17, vcc, 0, v15, vcc
	global_load_dword v41, v[16:17], off nt
	v_add_co_u32_e32 v16, vcc, s5, v14
	s_mov_b32 s5, 0x64000
	s_nop 0
	v_addc_co_u32_e32 v17, vcc, 0, v15, vcc
	global_load_dword v42, v[16:17], off nt
	v_add_co_u32_e32 v16, vcc, s5, v14
	s_mov_b32 s5, 0x68000
	s_nop 0
	v_addc_co_u32_e32 v17, vcc, 0, v15, vcc
	global_load_dword v43, v[16:17], off nt
	v_add_co_u32_e32 v16, vcc, s5, v14
	s_mov_b32 s5, 0x6c000
	s_nop 0
	v_addc_co_u32_e32 v17, vcc, 0, v15, vcc
	global_load_dword v44, v[16:17], off nt
	v_add_co_u32_e32 v16, vcc, s5, v14
	s_mov_b32 s5, 0x70000
	s_nop 0
	v_addc_co_u32_e32 v17, vcc, 0, v15, vcc
	global_load_dword v45, v[16:17], off nt
	v_add_co_u32_e32 v16, vcc, s5, v14
	s_mov_b32 s5, 0x74000
	s_nop 0
	v_addc_co_u32_e32 v17, vcc, 0, v15, vcc
	global_load_dword v46, v[16:17], off nt
	v_add_co_u32_e32 v16, vcc, s5, v14
	s_mov_b32 s5, 0x78000
	s_nop 0
	v_addc_co_u32_e32 v17, vcc, 0, v15, vcc
	global_load_dword v47, v[16:17], off nt
	v_add_co_u32_e32 v16, vcc, s5, v14
	s_mov_b32 s5, 0x7c000
	s_nop 0
	v_addc_co_u32_e32 v17, vcc, 0, v15, vcc
	v_add_co_u32_e32 v14, vcc, s5, v14
	global_load_dword v16, v[16:17], off nt
	s_nop 0
	v_addc_co_u32_e32 v15, vcc, 0, v15, vcc
	global_load_dword v14, v[14:15], off nt
	v_add_u32_e32 v15, 0x400, v52
	s_waitcnt vmcnt(30)
	ds_write2_b32 v52, v18, v19 offset1:66
	s_waitcnt vmcnt(28)
	ds_write2_b32 v52, v20, v21 offset0:132 offset1:198
	s_waitcnt vmcnt(26)
	ds_write2_b32 v15, v22, v23 offset0:8 offset1:74
	s_waitcnt vmcnt(24)
	ds_write2_b32 v15, v24, v25 offset0:140 offset1:206
	v_add_u32_e32 v15, 0x800, v52
	s_waitcnt vmcnt(22)
	ds_write2_b32 v15, v26, v27 offset0:16 offset1:82
	s_waitcnt vmcnt(20)
	ds_write2_b32 v15, v28, v29 offset0:148 offset1:214
	v_add_u32_e32 v15, 0xc00, v52
	s_waitcnt vmcnt(18)
	ds_write2_b32 v15, v30, v31 offset0:24 offset1:90
	s_waitcnt vmcnt(16)
	ds_write2_b32 v15, v32, v33 offset0:156 offset1:222
	v_add_u32_e32 v15, 0x1000, v52
	s_waitcnt vmcnt(14)
	ds_write2_b32 v15, v34, v35 offset0:32 offset1:98
	s_waitcnt vmcnt(12)
	ds_write2_b32 v15, v36, v37 offset0:164 offset1:230
	v_add_u32_e32 v15, 0x1400, v52
	s_waitcnt vmcnt(10)
	ds_write2_b32 v15, v38, v39 offset0:40 offset1:106
	s_waitcnt vmcnt(8)
	ds_write2_b32 v15, v40, v41 offset0:172 offset1:238
	v_add_u32_e32 v15, 0x1800, v52
	s_waitcnt vmcnt(6)
	ds_write2_b32 v15, v42, v43 offset0:48 offset1:114
	s_waitcnt vmcnt(4)
	ds_write2_b32 v15, v44, v45 offset0:180 offset1:246
	v_add_u32_e32 v15, 0x1c00, v52
	s_waitcnt vmcnt(2)
	ds_write2_b32 v15, v46, v47 offset0:56 offset1:122
	s_waitcnt vmcnt(0)
	ds_write2_b32 v15, v16, v14 offset0:188 offset1:254
	s_waitcnt lgkmcnt(0)
	ds_read2_b32 v[20:21], v54 offset0:33 offset1:41
	ds_read2_b32 v[22:23], v54 offset1:8
	ds_read2_b32 v[24:25], v54 offset0:66 offset1:74
	ds_read2_b32 v[26:27], v54 offset0:99 offset1:107
	ds_read2_b32 v[28:29], v54 offset0:132 offset1:140
	ds_read2_b32 v[30:31], v54 offset0:165 offset1:173
	ds_read2_b32 v[32:33], v54 offset0:198 offset1:206
	ds_read2_b32 v[34:35], v54 offset0:231 offset1:239
	v_lshl_add_u64 v[18:19], s[26:27], 1, v[6:7]
	s_waitcnt lgkmcnt(6)
	v_cvt_pk_bf16_f32 v14, v22, v20
	v_or_b32_e32 v20, s4, v53
	v_lshlrev_b32_e32 v190, 14, v20
	v_or_b32_e32 v20, s4, v55
	s_waitcnt lgkmcnt(4)
	v_cvt_pk_bf16_f32 v15, v24, v26
	s_waitcnt lgkmcnt(2)
	v_cvt_pk_bf16_f32 v16, v28, v30
	s_waitcnt lgkmcnt(0)
	v_cvt_pk_bf16_f32 v17, v32, v34
	v_lshl_add_u64 v[36:37], v[18:19], 0, v[190:191]
	v_lshlrev_b32_e32 v190, 14, v20
	global_store_dwordx4 v[36:37], v[14:17], off nt
	s_nop 1
	v_cvt_pk_bf16_f32 v14, v23, v21
	v_cvt_pk_bf16_f32 v15, v25, v27
	v_cvt_pk_bf16_f32 v16, v29, v31
	v_cvt_pk_bf16_f32 v17, v33, v35
	v_lshl_add_u64 v[20:21], v[18:19], 0, v[190:191]
	global_store_dwordx4 v[20:21], v[14:17], off nt
	ds_read2_b32 v[20:21], v54 offset0:49 offset1:57
	ds_read2_b32 v[22:23], v54 offset0:16 offset1:24
	ds_read2_b32 v[24:25], v54 offset0:82 offset1:90
	ds_read2_b32 v[26:27], v54 offset0:115 offset1:123
	ds_read2_b32 v[28:29], v54 offset0:148 offset1:156
	ds_read2_b32 v[30:31], v54 offset0:181 offset1:189
	ds_read2_b32 v[32:33], v54 offset0:214 offset1:222
	ds_read2_b32 v[34:35], v54 offset0:247 offset1:255
	s_waitcnt lgkmcnt(6)
	v_cvt_pk_bf16_f32 v14, v22, v20
	v_or_b32_e32 v20, s4, v56
	v_lshlrev_b32_e32 v190, 14, v20
	v_or_b32_e32 v20, s4, v57
	s_waitcnt lgkmcnt(4)
	v_cvt_pk_bf16_f32 v15, v24, v26
	s_waitcnt lgkmcnt(2)
	v_cvt_pk_bf16_f32 v16, v28, v30
	s_waitcnt lgkmcnt(0)
	v_cvt_pk_bf16_f32 v17, v32, v34
	v_lshl_add_u64 v[36:37], v[18:19], 0, v[190:191]
	v_lshlrev_b32_e32 v190, 14, v20
	global_store_dwordx4 v[36:37], v[14:17], off nt
	v_lshl_add_u64 v[18:19], v[18:19], 0, v[190:191]
	s_mov_b64 s[4:5], 0
	v_cvt_pk_bf16_f32 v14, v23, v21
	v_cvt_pk_bf16_f32 v15, v25, v27
	v_cvt_pk_bf16_f32 v16, v29, v31
	v_cvt_pk_bf16_f32 v17, v33, v35
	global_store_dwordx4 v[18:19], v[14:17], off nt
	s_waitcnt lgkmcnt(0)

.LBB0_1073:
	s_waitcnt vmcnt(30)
	ds_write2_b32 v52, v14, v15 offset1:66
	s_waitcnt vmcnt(28)
	ds_write2_b32 v52, v16, v17 offset0:132 offset1:198
	v_add_u32_e32 v14, 0x400, v52
	s_waitcnt vmcnt(26)
	ds_write2_b32 v14, v18, v19 offset0:8 offset1:74
	s_waitcnt vmcnt(24)
	ds_write2_b32 v14, v20, v21 offset0:140 offset1:206
	v_add_u32_e32 v14, 0x800, v52
	s_waitcnt vmcnt(22)
	ds_write2_b32 v14, v22, v23 offset0:16 offset1:82
	s_waitcnt vmcnt(20)
	ds_write2_b32 v14, v24, v25 offset0:148 offset1:214
	v_add_u32_e32 v14, 0xc00, v52
	s_waitcnt vmcnt(18)
	ds_write2_b32 v14, v26, v27 offset0:24 offset1:90
	s_waitcnt vmcnt(16)
	ds_write2_b32 v14, v28, v29 offset0:156 offset1:222
	v_add_u32_e32 v14, 0x1000, v52
	s_waitcnt vmcnt(14)
	ds_write2_b32 v14, v30, v31 offset0:32 offset1:98
	s_waitcnt vmcnt(12)
	ds_write2_b32 v14, v32, v33 offset0:164 offset1:230
	v_add_u32_e32 v14, 0x1400, v52
	s_waitcnt vmcnt(10)
	ds_write2_b32 v14, v34, v35 offset0:40 offset1:106
	s_waitcnt vmcnt(8)
	ds_write2_b32 v14, v36, v37 offset0:172 offset1:238
	v_add_u32_e32 v14, 0x1800, v52
	s_waitcnt vmcnt(6)
	ds_write2_b32 v14, v40, v41 offset0:48 offset1:114
	s_waitcnt vmcnt(4)
	ds_write2_b32 v14, v42, v43 offset0:180 offset1:246
	v_add_u32_e32 v14, 0x1c00, v52
	s_waitcnt vmcnt(2)
	ds_write2_b32 v14, v44, v45 offset0:56 offset1:122
	s_waitcnt vmcnt(0)
	ds_write2_b32 v14, v46, v47 offset0:188 offset1:254
	s_waitcnt lgkmcnt(0)
	ds_read2_b32 v[18:19], v54 offset0:33 offset1:41
	ds_read2_b32 v[20:21], v54 offset1:8
	ds_read2_b32 v[22:23], v54 offset0:66 offset1:74
	ds_read2_b32 v[24:25], v54 offset0:99 offset1:107
	ds_read2_b32 v[26:27], v54 offset0:132 offset1:140
	ds_read2_b32 v[28:29], v54 offset0:165 offset1:173
	ds_read2_b32 v[30:31], v54 offset0:198 offset1:206
	ds_read2_b32 v[32:33], v54 offset0:231 offset1:239
	s_lshl_b32 s26, s5, 1
	s_waitcnt lgkmcnt(6)
	v_cvt_pk_bf16_f32 v14, v20, v18
	v_or_b32_e32 v18, s4, v53
	v_lshl_add_u64 v[34:35], v[8:9], 0, s[26:27]
	v_lshlrev_b32_e32 v190, 12, v18
	s_waitcnt lgkmcnt(4)
	v_cvt_pk_bf16_f32 v15, v22, v24
	s_waitcnt lgkmcnt(2)
	v_cvt_pk_bf16_f32 v16, v26, v28
	s_waitcnt lgkmcnt(0)
	v_cvt_pk_bf16_f32 v17, v30, v32
	v_lshl_add_u64 v[36:37], v[34:35], 0, v[190:191]
	global_store_dwordx4 v[36:37], v[14:17], off nt
	v_or_b32_e32 v18, s4, v55
	v_lshlrev_b32_e32 v190, 12, v18
	v_cvt_pk_bf16_f32 v14, v21, v19
	v_cvt_pk_bf16_f32 v15, v23, v25
	v_cvt_pk_bf16_f32 v16, v27, v29
	v_cvt_pk_bf16_f32 v17, v31, v33
	ds_read2_b32 v[20:21], v54 offset0:49 offset1:57
	ds_read2_b32 v[22:23], v54 offset0:16 offset1:24
	ds_read2_b32 v[24:25], v54 offset0:82 offset1:90
	ds_read2_b32 v[26:27], v54 offset0:115 offset1:123
	ds_read2_b32 v[28:29], v54 offset0:148 offset1:156
	ds_read2_b32 v[30:31], v54 offset0:181 offset1:189
	ds_read2_b32 v[32:33], v54 offset0:214 offset1:222
	ds_read2_b32 v[36:37], v54 offset0:247 offset1:255
	v_lshl_add_u64 v[18:19], v[34:35], 0, v[190:191]
	global_store_dwordx4 v[18:19], v[14:17], off nt
	v_or_b32_e32 v18, s4, v56
	v_lshlrev_b32_e32 v190, 12, v18
	s_waitcnt lgkmcnt(6)
	v_cvt_pk_bf16_f32 v14, v22, v20
	s_waitcnt lgkmcnt(4)
	v_cvt_pk_bf16_f32 v15, v24, v26
	s_waitcnt lgkmcnt(2)
	v_cvt_pk_bf16_f32 v16, v28, v30
	s_waitcnt lgkmcnt(0)
	v_cvt_pk_bf16_f32 v17, v32, v36
	v_lshl_add_u64 v[18:19], v[34:35], 0, v[190:191]
	global_store_dwordx4 v[18:19], v[14:17], off nt
	v_or_b32_e32 v18, s4, v57
	v_lshlrev_b32_e32 v190, 12, v18
	v_cvt_pk_bf16_f32 v14, v23, v21
	v_cvt_pk_bf16_f32 v15, v25, v27
	v_cvt_pk_bf16_f32 v16, v29, v31
	v_cvt_pk_bf16_f32 v17, v33, v37
	v_lshl_add_u64 v[18:19], v[34:35], 0, v[190:191]
	global_store_dwordx4 v[18:19], v[14:17], off nt
	s_waitcnt lgkmcnt(0)

.LBB0_1075:
	s_andn2_b64 vcc, exec, s[4:5]
	s_cbranch_vccnz .LBB0_1077
	s_add_i32 s4, s1, 0xe500
	s_and_b32 s5, s4, 0xffc0
	s_and_b32 s4, s21, 0x7e0
	v_or_b32_e32 v14, s5, v51
	v_or_b32_e32 v16, s4, v50
	v_lshlrev_b32_e32 v190, 13, v14
	v_lshl_add_u64 v[14:15], s[40:41], 0, v[190:191]
	v_lshlrev_b32_e32 v190, 2, v16
	v_lshl_add_u64 v[14:15], v[14:15], 0, v[190:191]
	v_add_co_u32_e32 v16, vcc, 0x4000, v14
	global_load_dword v18, v[14:15], off nt
	s_nop 0
	v_addc_co_u32_e32 v17, vcc, 0, v15, vcc
	global_load_dword v19, v[16:17], off nt
	v_add_co_u32_e32 v16, vcc, 0x8000, v14
	s_mov_b32 s26, 0x10000
	s_nop 0
	v_addc_co_u32_e32 v17, vcc, 0, v15, vcc
	global_load_dword v20, v[16:17], off nt
	v_add_co_u32_e32 v16, vcc, 0xc000, v14
	s_nop 1
	v_addc_co_u32_e32 v17, vcc, 0, v15, vcc
	global_load_dword v21, v[16:17], off nt
	v_add_co_u32_e32 v16, vcc, s26, v14
	s_mov_b32 s26, 0x14000
	s_nop 0
	v_addc_co_u32_e32 v17, vcc, 0, v15, vcc
	global_load_dword v22, v[16:17], off nt
	v_add_co_u32_e32 v16, vcc, s26, v14
	s_mov_b32 s26, 0x18000
	s_nop 0
	v_addc_co_u32_e32 v17, vcc, 0, v15, vcc
	global_load_dword v23, v[16:17], off nt
	v_add_co_u32_e32 v16, vcc, s26, v14
	s_mov_b32 s26, 0x1c000
	s_nop 0
	v_addc_co_u32_e32 v17, vcc, 0, v15, vcc
	global_load_dword v24, v[16:17], off nt
	v_add_co_u32_e32 v16, vcc, s26, v14
	s_mov_b32 s26, 0x20000
	s_nop 0
	v_addc_co_u32_e32 v17, vcc, 0, v15, vcc
	global_load_dword v25, v[16:17], off nt
	v_add_co_u32_e32 v16, vcc, s26, v14
	s_mov_b32 s26, 0x24000
	s_nop 0
	v_addc_co_u32_e32 v17, vcc, 0, v15, vcc
	global_load_dword v26, v[16:17], off nt
	v_add_co_u32_e32 v16, vcc, s26, v14
	s_mov_b32 s26, 0x28000
	s_nop 0
	v_addc_co_u32_e32 v17, vcc, 0, v15, vcc
	global_load_dword v27, v[16:17], off nt
	v_add_co_u32_e32 v16, vcc, s26, v14
	s_mov_b32 s26, 0x2c000
	s_nop 0
	v_addc_co_u32_e32 v17, vcc, 0, v15, vcc
	global_load_dword v28, v[16:17], off nt
	v_add_co_u32_e32 v16, vcc, s26, v14
	s_mov_b32 s26, 0x30000
	s_nop 0
	v_addc_co_u32_e32 v17, vcc, 0, v15, vcc
	global_load_dword v29, v[16:17], off nt
	v_add_co_u32_e32 v16, vcc, s26, v14
	s_mov_b32 s26, 0x34000
	s_nop 0
	v_addc_co_u32_e32 v17, vcc, 0, v15, vcc
	global_load_dword v30, v[16:17], off nt
	v_add_co_u32_e32 v16, vcc, s26, v14
	s_mov_b32 s26, 0x38000
	s_nop 0
	v_addc_co_u32_e32 v17, vcc, 0, v15, vcc
	global_load_dword v31, v[16:17], off nt
	v_add_co_u32_e32 v16, vcc, s26, v14
	s_mov_b32 s26, 0x3c000
	s_nop 0
	v_addc_co_u32_e32 v17, vcc, 0, v15, vcc
	global_load_dword v32, v[16:17], off nt
	v_add_co_u32_e32 v16, vcc, s26, v14
	s_mov_b32 s26, 0x40000
	s_nop 0
	v_addc_co_u32_e32 v17, vcc, 0, v15, vcc
	global_load_dword v33, v[16:17], off nt
	v_add_co_u32_e32 v16, vcc, s26, v14
	s_mov_b32 s26, 0x44000
	s_nop 0
	v_addc_co_u32_e32 v17, vcc, 0, v15, vcc
	global_load_dword v34, v[16:17], off nt
	v_add_co_u32_e32 v16, vcc, s26, v14
	s_mov_b32 s26, 0x48000
	s_nop 0
	v_addc_co_u32_e32 v17, vcc, 0, v15, vcc
	global_load_dword v35, v[16:17], off nt
	v_add_co_u32_e32 v16, vcc, s26, v14
	s_mov_b32 s26, 0x4c000
	s_nop 0
	v_addc_co_u32_e32 v17, vcc, 0, v15, vcc
	global_load_dword v36, v[16:17], off nt
	v_add_co_u32_e32 v16, vcc, s26, v14
	s_mov_b32 s26, 0x50000
	s_nop 0
	v_addc_co_u32_e32 v17, vcc, 0, v15, vcc
	global_load_dword v37, v[16:17], off nt
	v_add_co_u32_e32 v16, vcc, s26, v14
	s_mov_b32 s26, 0x54000
	s_nop 0
	v_addc_co_u32_e32 v17, vcc, 0, v15, vcc
	global_load_dword v38, v[16:17], off nt
	v_add_co_u32_e32 v16, vcc, s26, v14
	s_mov_b32 s26, 0x58000
	s_nop 0
	v_addc_co_u32_e32 v17, vcc, 0, v15, vcc
	global_load_dword v39, v[16:17], off nt
	v_add_co_u32_e32 v16, vcc, s26, v14
	s_mov_b32 s26, 0x5c000
	s_nop 0
	v_addc_co_u32_e32 v17, vcc, 0, v15, vcc
	global_load_dword v40, v[16:17], off nt
	v_add_co_u32_e32 v16, vcc, s26, v14
	s_mov_b32 s26, 0x60000
	s_nop 0
	v_addc_co_u32_e32 v17, vcc, 0, v15, vcc
	global_load_dword v41, v[16:17], off nt
	v_add_co_u32_e32 v16, vcc, s26, v14
	s_mov_b32 s26, 0x64000
	s_nop 0
	v_addc_co_u32_e32 v17, vcc, 0, v15, vcc
	global_load_dword v42, v[16:17], off nt
	v_add_co_u32_e32 v16, vcc, s26, v14
	s_mov_b32 s26, 0x68000
	s_nop 0
	v_addc_co_u32_e32 v17, vcc, 0, v15, vcc
	global_load_dword v43, v[16:17], off nt
	v_add_co_u32_e32 v16, vcc, s26, v14
	s_mov_b32 s26, 0x6c000
	s_nop 0
	v_addc_co_u32_e32 v17, vcc, 0, v15, vcc
	global_load_dword v44, v[16:17], off nt
	v_add_co_u32_e32 v16, vcc, s26, v14
	s_mov_b32 s26, 0x70000
	s_nop 0
	v_addc_co_u32_e32 v17, vcc, 0, v15, vcc
	global_load_dword v45, v[16:17], off nt
	v_add_co_u32_e32 v16, vcc, s26, v14
	s_mov_b32 s26, 0x74000
	s_nop 0
	v_addc_co_u32_e32 v17, vcc, 0, v15, vcc
	global_load_dword v46, v[16:17], off nt
	v_add_co_u32_e32 v16, vcc, s26, v14
	s_mov_b32 s26, 0x78000
	s_nop 0
	v_addc_co_u32_e32 v17, vcc, 0, v15, vcc
	global_load_dword v47, v[16:17], off nt
	v_add_co_u32_e32 v16, vcc, s26, v14
	s_mov_b32 s26, 0x7c000
	s_nop 0
	v_addc_co_u32_e32 v17, vcc, 0, v15, vcc
	v_add_co_u32_e32 v14, vcc, s26, v14
	global_load_dword v16, v[16:17], off nt
	s_nop 0
	v_addc_co_u32_e32 v15, vcc, 0, v15, vcc
	global_load_dword v14, v[14:15], off nt
	v_add_u32_e32 v15, 0x400, v52
	s_waitcnt vmcnt(30)
	ds_write2_b32 v52, v18, v19 offset1:66
	s_waitcnt vmcnt(28)
	ds_write2_b32 v52, v20, v21 offset0:132 offset1:198
	s_waitcnt vmcnt(26)
	ds_write2_b32 v15, v22, v23 offset0:8 offset1:74
	s_waitcnt vmcnt(24)
	ds_write2_b32 v15, v24, v25 offset0:140 offset1:206
	v_add_u32_e32 v15, 0x800, v52
	s_waitcnt vmcnt(22)
	ds_write2_b32 v15, v26, v27 offset0:16 offset1:82
	s_waitcnt vmcnt(20)
	ds_write2_b32 v15, v28, v29 offset0:148 offset1:214
	v_add_u32_e32 v15, 0xc00, v52
	s_waitcnt vmcnt(18)
	ds_write2_b32 v15, v30, v31 offset0:24 offset1:90
	s_waitcnt vmcnt(16)
	ds_write2_b32 v15, v32, v33 offset0:156 offset1:222
	v_add_u32_e32 v15, 0x1000, v52
	s_waitcnt vmcnt(14)
	ds_write2_b32 v15, v34, v35 offset0:32 offset1:98
	s_waitcnt vmcnt(12)
	ds_write2_b32 v15, v36, v37 offset0:164 offset1:230
	v_add_u32_e32 v15, 0x1400, v52
	s_waitcnt vmcnt(10)
	ds_write2_b32 v15, v38, v39 offset0:40 offset1:106
	s_waitcnt vmcnt(8)
	ds_write2_b32 v15, v40, v41 offset0:172 offset1:238
	v_add_u32_e32 v15, 0x1800, v52
	s_waitcnt vmcnt(6)
	ds_write2_b32 v15, v42, v43 offset0:48 offset1:114
	s_waitcnt vmcnt(4)
	ds_write2_b32 v15, v44, v45 offset0:180 offset1:246
	v_add_u32_e32 v15, 0x1c00, v52
	s_waitcnt vmcnt(2)
	ds_write2_b32 v15, v46, v47 offset0:56 offset1:122
	s_waitcnt vmcnt(0)
	ds_write2_b32 v15, v16, v14 offset0:188 offset1:254
	s_waitcnt lgkmcnt(0)
	ds_read2_b32 v[20:21], v54 offset0:33 offset1:41
	ds_read2_b32 v[22:23], v54 offset1:8
	ds_read2_b32 v[24:25], v54 offset0:66 offset1:74
	ds_read2_b32 v[26:27], v54 offset0:99 offset1:107
	ds_read2_b32 v[28:29], v54 offset0:132 offset1:140
	ds_read2_b32 v[30:31], v54 offset0:165 offset1:173
	ds_read2_b32 v[32:33], v54 offset0:198 offset1:206
	ds_read2_b32 v[34:35], v54 offset0:231 offset1:239
	s_lshl_b32 s26, s5, 1
	s_waitcnt lgkmcnt(6)
	v_cvt_pk_bf16_f32 v14, v22, v20
	v_or_b32_e32 v20, s4, v53
	v_lshl_add_u64 v[18:19], v[10:11], 0, s[26:27]
	v_lshlrev_b32_e32 v190, 12, v20
	v_or_b32_e32 v20, s4, v55
	s_waitcnt lgkmcnt(4)
	v_cvt_pk_bf16_f32 v15, v24, v26
	s_waitcnt lgkmcnt(2)
	v_cvt_pk_bf16_f32 v16, v28, v30
	s_waitcnt lgkmcnt(0)
	v_cvt_pk_bf16_f32 v17, v32, v34
	v_lshl_add_u64 v[36:37], v[18:19], 0, v[190:191]
	v_lshlrev_b32_e32 v190, 12, v20
	global_store_dwordx4 v[36:37], v[14:17], off nt
	s_nop 1
	v_cvt_pk_bf16_f32 v14, v23, v21
	v_cvt_pk_bf16_f32 v15, v25, v27
	v_cvt_pk_bf16_f32 v16, v29, v31
	v_cvt_pk_bf16_f32 v17, v33, v35
	v_lshl_add_u64 v[20:21], v[18:19], 0, v[190:191]
	global_store_dwordx4 v[20:21], v[14:17], off nt
	ds_read2_b32 v[20:21], v54 offset0:49 offset1:57
	ds_read2_b32 v[22:23], v54 offset0:16 offset1:24
	ds_read2_b32 v[24:25], v54 offset0:82 offset1:90
	ds_read2_b32 v[26:27], v54 offset0:115 offset1:123
	ds_read2_b32 v[28:29], v54 offset0:148 offset1:156
	ds_read2_b32 v[30:31], v54 offset0:181 offset1:189
	ds_read2_b32 v[32:33], v54 offset0:214 offset1:222
	ds_read2_b32 v[34:35], v54 offset0:247 offset1:255
	s_waitcnt lgkmcnt(6)
	v_cvt_pk_bf16_f32 v14, v22, v20
	v_or_b32_e32 v20, s4, v56
	v_lshlrev_b32_e32 v190, 12, v20
	v_or_b32_e32 v20, s4, v57
	s_waitcnt lgkmcnt(4)
	v_cvt_pk_bf16_f32 v15, v24, v26
	s_waitcnt lgkmcnt(2)
	v_cvt_pk_bf16_f32 v16, v28, v30
	s_waitcnt lgkmcnt(0)
	v_cvt_pk_bf16_f32 v17, v32, v34
	v_lshl_add_u64 v[36:37], v[18:19], 0, v[190:191]
	v_lshlrev_b32_e32 v190, 12, v20
	global_store_dwordx4 v[36:37], v[14:17], off nt
	v_lshl_add_u64 v[18:19], v[18:19], 0, v[190:191]
	s_nop 0
	v_cvt_pk_bf16_f32 v14, v23, v21
	v_cvt_pk_bf16_f32 v15, v25, v27
	v_cvt_pk_bf16_f32 v16, v29, v31
	v_cvt_pk_bf16_f32 v17, v33, v35
	global_store_dwordx4 v[18:19], v[14:17], off nt
	s_waitcnt lgkmcnt(0)

.LBB0_1145:
	v_readlane_b32 s0, v255, 63
	s_nop 3
	s_cmp_eq_u32 s0, 1
	s_cbranch_scc0 .Lp1_done
	v_writelane_b32 v255, 2, 63
	s_waitcnt vmcnt(0) lgkmcnt(0)
	s_barrier
	s_branch .Lp1_gemm
